# adds: HGRN passB loads batched per 8 steps; mixer-norm (P5D) next-row loads kept in flight
# speedup vs baseline: 1.0073x; 1.0073x over previous
; __device__ __forceinline__ unsigned pk2(float lo, float hi) { f32x2 v = {lo, hi}; bf16x2_t b = __builtin_convertvector(v, bf16x2_t); return __builtin_bit_cast(unsigned, b); }
; __device__ __forceinline__ float bflo(unsigned w) { return __uint_as_float(w << 16); }
; __device__ __forceinline__ float bfhi(unsigned w) { return __uint_as_float(w & 0xffff0000u); }
; __device__ __forceinline__ void hgrn_passB(const bf16* UT, const float* DC, bf16* ST, float* PH, int gtid, int gthreads) {
;     for (int e = gtid; e < 32 * 4096; e += gthreads) { const int seq = e >> 12, rem = e & 4095, dv = rem >> 5, dk = (rem & 31) * 4;
;         f32x4 S = (f32x4){0.f, 0.f, 0.f, 0.f};
; #pragma unroll 8
;         for (int c = 0; c < 16; ++c) { const size_t u = (size_t)seq * 16 + c;
;             const u32x2 uw = *(const u32x2*)(UT + u * 16384 + dv * 128 + dk); const f32x4 U = (f32x4){bflo(uw.x), bfhi(uw.x), bflo(uw.y), bfhi(uw.y)}, Dv = *(const f32x4*)(DC + u * 128 + dk);
;             u32x2 w; w.x = pk2(S[0], S[1]); w.y = pk2(S[2], S[3]); *(u32x2*)(ST + u * 16384 + dv * 128 + dk) = w;
;             S = Dv * S + U; }
; #pragma unroll
;         for (int j = 0; j < 4; ++j) PH[(size_t)seq * 16384 + (dk + j) * 128 + dv] = S[j];
;     }
.LBB0_689:
	v_lshl_add_u64 v[10:11], s[92:93], 0, v[8:9]
	v_lshl_add_u64 v[12:13], s[92:93], 0, v[6:7]
	v_add_co_u32_e32 v20, vcc, 0x16f00000, v10
	s_nop 1
	v_addc_co_u32_e32 v21, vcc, 0, v11, vcc
	v_add_co_u32_e32 v12, vcc, 0x6e00000, v12
	s_nop 1
	v_addc_co_u32_e32 v13, vcc, 0, v13, vcc
	v_add_co_u32_e32 v10, vcc, 0x25700000, v10
	s_nop 1
	v_addc_co_u32_e32 v11, vcc, 0, v11, vcc
	s_mov_b64 s[8:9], 0x8000
	global_load_dwordx2 v[32:33], v[20:21], off
	v_lshl_add_u64 v[20:21], v[20:21], 0, s[8:9]
	global_load_dwordx2 v[34:35], v[20:21], off
	v_lshl_add_u64 v[20:21], v[20:21], 0, s[8:9]
	global_load_dwordx2 v[36:37], v[20:21], off
	v_lshl_add_u64 v[20:21], v[20:21], 0, s[8:9]
	global_load_dwordx2 v[38:39], v[20:21], off
	v_lshl_add_u64 v[20:21], v[20:21], 0, s[8:9]
	global_load_dwordx2 v[40:41], v[20:21], off
	v_lshl_add_u64 v[20:21], v[20:21], 0, s[8:9]
	global_load_dwordx2 v[42:43], v[20:21], off
	v_lshl_add_u64 v[20:21], v[20:21], 0, s[8:9]
	global_load_dwordx2 v[44:45], v[20:21], off
	v_lshl_add_u64 v[20:21], v[20:21], 0, s[8:9]
	global_load_dwordx2 v[46:47], v[20:21], off
	global_load_dwordx4 v[48:51], v[12:13], off
	global_load_dwordx4 v[52:55], v[12:13], off offset:512
	global_load_dwordx4 v[56:59], v[12:13], off offset:1024
	global_load_dwordx4 v[60:63], v[12:13], off offset:1536
	global_load_dwordx4 v[64:67], v[12:13], off offset:2048
	global_load_dwordx4 v[86:89], v[12:13], off offset:2560
	global_load_dwordx4 v[90:93], v[12:13], off offset:3072
	global_load_dwordx4 v[94:97], v[12:13], off offset:3584
	v_cvt_pk_bf16_f32 v28, v16, v17
	v_cvt_pk_bf16_f32 v29, v14, v15
	s_waitcnt vmcnt(7)
	v_lshlrev_b32_e32 v24, 16, v32
	v_and_b32_e32 v25, 0xffff0000, v32
	v_lshlrev_b32_e32 v26, 16, v33
	v_and_b32_e32 v27, 0xffff0000, v33
	global_store_dwordx2 v[10:11], v[28:29], off
	v_pk_fma_f32 v[16:17], v[16:17], v[48:49], v[24:25]
	v_pk_fma_f32 v[14:15], v[14:15], v[50:51], v[26:27]
	v_lshl_add_u64 v[10:11], v[10:11], 0, s[8:9]
	v_cvt_pk_bf16_f32 v30, v16, v17
	v_cvt_pk_bf16_f32 v31, v14, v15
	s_waitcnt vmcnt(7)
	v_lshlrev_b32_e32 v24, 16, v34
	v_and_b32_e32 v25, 0xffff0000, v34
	v_lshlrev_b32_e32 v26, 16, v35
	v_and_b32_e32 v27, 0xffff0000, v35
	global_store_dwordx2 v[10:11], v[30:31], off
	v_pk_fma_f32 v[16:17], v[16:17], v[52:53], v[24:25]
	v_pk_fma_f32 v[14:15], v[14:15], v[54:55], v[26:27]
	v_lshl_add_u64 v[10:11], v[10:11], 0, s[8:9]
	v_cvt_pk_bf16_f32 v28, v16, v17
	v_cvt_pk_bf16_f32 v29, v14, v15
	s_waitcnt vmcnt(7)
	v_lshlrev_b32_e32 v24, 16, v36
	v_and_b32_e32 v25, 0xffff0000, v36
	v_lshlrev_b32_e32 v26, 16, v37
	v_and_b32_e32 v27, 0xffff0000, v37
	global_store_dwordx2 v[10:11], v[28:29], off
	v_pk_fma_f32 v[16:17], v[16:17], v[56:57], v[24:25]
	v_pk_fma_f32 v[14:15], v[14:15], v[58:59], v[26:27]
	v_lshl_add_u64 v[10:11], v[10:11], 0, s[8:9]
	v_cvt_pk_bf16_f32 v30, v16, v17
	v_cvt_pk_bf16_f32 v31, v14, v15
	s_waitcnt vmcnt(7)
	v_lshlrev_b32_e32 v24, 16, v38
	v_and_b32_e32 v25, 0xffff0000, v38
	v_lshlrev_b32_e32 v26, 16, v39
	v_and_b32_e32 v27, 0xffff0000, v39
	global_store_dwordx2 v[10:11], v[30:31], off
	v_pk_fma_f32 v[16:17], v[16:17], v[60:61], v[24:25]
	v_pk_fma_f32 v[14:15], v[14:15], v[62:63], v[26:27]
	v_lshl_add_u64 v[10:11], v[10:11], 0, s[8:9]
	v_cvt_pk_bf16_f32 v28, v16, v17
	v_cvt_pk_bf16_f32 v29, v14, v15
	s_waitcnt vmcnt(7)
	v_lshlrev_b32_e32 v24, 16, v40
	v_and_b32_e32 v25, 0xffff0000, v40
	v_lshlrev_b32_e32 v26, 16, v41
	v_and_b32_e32 v27, 0xffff0000, v41
	global_store_dwordx2 v[10:11], v[28:29], off
	v_pk_fma_f32 v[16:17], v[16:17], v[64:65], v[24:25]
	v_pk_fma_f32 v[14:15], v[14:15], v[66:67], v[26:27]
	v_lshl_add_u64 v[10:11], v[10:11], 0, s[8:9]
	v_cvt_pk_bf16_f32 v30, v16, v17
	v_cvt_pk_bf16_f32 v31, v14, v15
	s_waitcnt vmcnt(7)
	v_lshlrev_b32_e32 v24, 16, v42
	v_and_b32_e32 v25, 0xffff0000, v42
	v_lshlrev_b32_e32 v26, 16, v43
	v_and_b32_e32 v27, 0xffff0000, v43
	global_store_dwordx2 v[10:11], v[30:31], off
	v_pk_fma_f32 v[16:17], v[16:17], v[86:87], v[24:25]
	v_pk_fma_f32 v[14:15], v[14:15], v[88:89], v[26:27]
	v_lshl_add_u64 v[10:11], v[10:11], 0, s[8:9]
	v_cvt_pk_bf16_f32 v28, v16, v17
	v_cvt_pk_bf16_f32 v29, v14, v15
	s_waitcnt vmcnt(7)
	v_lshlrev_b32_e32 v24, 16, v44
	v_and_b32_e32 v25, 0xffff0000, v44
	v_lshlrev_b32_e32 v26, 16, v45
	v_and_b32_e32 v27, 0xffff0000, v45
	global_store_dwordx2 v[10:11], v[28:29], off
	v_pk_fma_f32 v[16:17], v[16:17], v[90:91], v[24:25]
	v_pk_fma_f32 v[14:15], v[14:15], v[92:93], v[26:27]
	v_lshl_add_u64 v[10:11], v[10:11], 0, s[8:9]
	v_cvt_pk_bf16_f32 v30, v16, v17
	v_cvt_pk_bf16_f32 v31, v14, v15
	s_waitcnt vmcnt(7)
	v_lshlrev_b32_e32 v24, 16, v46
	v_and_b32_e32 v25, 0xffff0000, v46
	v_lshlrev_b32_e32 v26, 16, v47
	v_and_b32_e32 v27, 0xffff0000, v47
	global_store_dwordx2 v[10:11], v[30:31], off
	v_pk_fma_f32 v[16:17], v[16:17], v[94:95], v[24:25]
	v_pk_fma_f32 v[14:15], v[14:15], v[96:97], v[26:27]
	v_lshl_add_u64 v[10:11], v[10:11], 0, s[8:9]
	s_mov_b64 s[8:9], 0x1000
	v_lshl_add_u64 v[6:7], v[6:7], 0, s[8:9]
	s_mov_b64 s[8:9], 0x40000
	v_lshl_add_u64 v[8:9], v[8:9], 0, s[8:9]
	s_add_i32 s3, s3, -8
	s_cmp_eq_u32 s3, 0
	s_cbranch_scc0 .LBB0_689
	v_and_b32_e32 v2, 0x7f, v2
	v_lshlrev_b64 v[4:5], 16, v[4:5]
	v_lshl_add_u64 v[4:5], s[0:1], 0, v[4:5]
	v_lshlrev_b32_e32 v2, 2, v2
	v_lshl_add_u64 v[4:5], v[4:5], 0, v[2:3]
	v_lshlrev_b32_e32 v2, 11, v19
	v_add_u32_e32 v19, s50, v19
	s_mov_b32 s3, 0x1ffff
	v_and_b32_e32 v2, 0xf800, v2
	v_cmp_lt_i32_e32 vcc, s3, v19
	v_lshl_add_u64 v[4:5], v[4:5], 0, v[2:3]
	s_or_b64 s[6:7], vcc, s[6:7]
	v_add_u32_e32 v18, s2, v18
	global_store_dword v[4:5], v16, off
	global_store_dword v[4:5], v17, off offset:512
	global_store_dword v[4:5], v14, off offset:1024
	global_store_dword v[4:5], v15, off offset:1536
	s_andn2_b64 exec, exec, s[6:7]
	s_cbranch_execnz .LBB0_688

; __device__ __forceinline__ void mix_norm_rows(bf16* HB, const bf16* Z, const float* ga, const float* gh, int gw, int NGW, int lane) {
;     float gav[16], ghv[16];
; #pragma unroll
;     for (int i = 0; i < 8; ++i) { gav[i] = ga[lane * 8 + i]; gav[8 + i] = ga[512 + lane * 8 + i]; }
; #pragma unroll
;     for (int i = 0; i < 16; ++i) ghv[i] = gh[(lane & 7) * 16 + i];
;     int row = gw;
;     u32x4 c[6], n[6];
; #pragma unroll
;     for (int i = 0; i < 6; ++i) { c[i] = (u32x4){0u, 0u, 0u, 0u}; n[i] = c[i]; }
;     if (row < MT) { const bf16* hr = HB + (size_t)row * DM; const bf16* zr = Z + (size_t)row * NIN + ZHG + lane * 16;
;         c[0] = *(const u32x4*)(hr + lane * 8); c[1] = *(const u32x4*)(hr + 512 + lane * 8); c[2] = *(const u32x4*)(hr + 1024 + lane * 16); c[3] = *(const u32x4*)(hr + 1024 + lane * 16 + 8);
;         c[4] = *(const u32x4*)zr; c[5] = *(const u32x4*)(zr + 8); }
.LBB0_802:
	s_or_b64 exec, exec, s[0:1]
	v_readlane_b32 s0, v255, 20
	v_readlane_b32 s1, v255, 21
	s_and_b64 vcc, exec, s[0:1]
	v_mov_b32_e32 v19, 0
	s_waitcnt lgkmcnt(0)
	s_barrier
	s_cbranch_vccnz .LBB0_808
	v_readlane_b32 s0, v254, 29
	v_readlane_b32 s1, v254, 30
	v_readlane_b32 s2, v254, 31
	v_readlane_b32 s3, v254, 32
	s_ashr_i32 s77, s76, 31
	v_lshlrev_b32_e32 v18, 6, v165
	s_lshl_b64 s[2:3], s[76:77], 12
	v_readlane_b32 s0, v254, 62
	v_lshlrev_b32_e32 v14, 2, v164
	v_readlane_b32 s4, v254, 33
	v_readlane_b32 s5, v254, 34
	v_readlane_b32 s6, v254, 35
	v_readlane_b32 s7, v254, 36
	v_and_b32_e32 v18, 0x1c0, v18
	v_readlane_b32 s1, v254, 63
	s_add_u32 s0, s0, s2
	global_load_dwordx4 v[2:5], v14, s[4:5] offset:16
	global_load_dwordx4 v[6:9], v14, s[4:5]
	global_load_dwordx4 v[10:13], v14, s[4:5] offset:2064
	s_nop 0
	global_load_dwordx4 v[14:17], v14, s[4:5] offset:2048
	s_nop 0
	global_load_dwordx4 v[22:25], v18, s[6:7] offset:48
	global_load_dwordx4 v[26:29], v18, s[6:7] offset:32
	global_load_dwordx4 v[30:33], v18, s[6:7] offset:16
	global_load_dwordx4 v[34:37], v18, s[6:7]
	s_addc_u32 s1, s1, s3
	s_mul_i32 s4, s76, 0x2c00
	v_readlane_b32 s6, v255, 0
	s_mul_hi_i32 s5, s76, 0x2c00
	v_readlane_b32 s7, v255, 1
	s_add_u32 s4, s6, s4
	s_addc_u32 s5, s7, s5
	v_lshlrev_b32_e32 v18, 5, v165
	v_lshl_add_u64 v[20:21], s[4:5], 0, v[18:19]
	s_mov_b64 s[4:5], 0x2400
	v_lshl_add_u64 v[38:39], v[20:21], 0, s[4:5]
	s_movk_i32 s4, 0x2000
	v_lshlrev_b32_e32 v40, 1, v164
	v_add_co_u32_e32 v20, vcc, s4, v20
	global_load_dwordx4 v[66:69], v18, s[0:1] offset:2064
	global_load_dwordx4 v[62:65], v18, s[0:1] offset:2048
	v_addc_co_u32_e32 v21, vcc, 0, v21, vcc
	global_load_dwordx4 v[78:81], v40, s[0:1] offset:1024
	global_load_dwordx4 v[58:61], v[20:21], off offset:1024
	global_load_dwordx4 v[74:77], v40, s[0:1]
	global_load_dwordx4 v[70:73], v[38:39], off offset:16
	v_mbcnt_lo_u32_b32 v21, -1, 0
	v_mbcnt_hi_u32_b32 v21, -1, v21
	v_and_b32_e32 v38, 64, v21
	v_add_u32_e32 v38, 64, v38
	v_xor_b32_e32 v39, 1, v21
	v_cmp_lt_i32_e32 vcc, v39, v38
	v_lshlrev_b32_e32 v20, 4, v165
	v_or_b32_e32 v82, s2, v18
	v_cndmask_b32_e32 v39, v21, v39, vcc
	v_lshlrev_b32_e32 v93, 2, v39
	v_xor_b32_e32 v39, 2, v21
	v_cmp_lt_i32_e32 vcc, v39, v38
	v_mov_b32_e32 v83, s3
	v_or_b32_e32 v84, s2, v20
	v_cndmask_b32_e32 v39, v21, v39, vcc
	v_lshlrev_b32_e32 v114, 2, v39
	v_xor_b32_e32 v39, 4, v21
	v_cmp_lt_i32_e32 vcc, v39, v38
	v_mov_b32_e32 v85, s3
	s_ashr_i32 s73, s72, 31
	v_cndmask_b32_e32 v39, v21, v39, vcc
	v_lshlrev_b32_e32 v115, 2, v39
	v_xor_b32_e32 v39, 8, v21
	v_cmp_lt_i32_e32 vcc, v39, v38
	v_readlane_b32 s10, v254, 39
	s_ashr_i32 s97, s96, 31
	v_cndmask_b32_e32 v39, v21, v39, vcc
	v_lshlrev_b32_e32 v116, 2, v39
	v_xor_b32_e32 v39, 16, v21
	v_cmp_lt_i32_e32 vcc, v39, v38
	s_brev_b32 s6, 60
	s_lshl_b64 s[0:1], s[96:97], 12
	v_cndmask_b32_e32 v39, v21, v39, vcc
	v_lshlrev_b32_e32 v117, 2, v39
	v_xor_b32_e32 v39, 32, v21
	v_cmp_lt_i32_e32 vcc, v39, v38
	s_mul_hi_i32 s5, s96, 0x2c00
	s_mul_i32 s4, s96, 0x2c00
	v_cndmask_b32_e32 v21, v21, v39, vcc
	v_lshlrev_b32_e32 v118, 2, v21
	v_mov_b32_e32 v21, 0x2c00
	v_mad_i64_i32 v[86:87], s[2:3], s72, v21, v[18:19]
	s_lshl_b64 s[2:3], s[72:73], 12
	s_nop 0
	v_or_b32_e32 v90, s2, v20
	v_mov_b32_e32 v20, v19
	v_mov_b32_e32 v21, v19
	v_or_b32_e32 v88, s2, v18
	v_mov_b32_e32 v18, v19
	v_mov_b64_e32 v[40:41], v[20:21]
	v_mov_b64_e32 v[48:49], v[20:21]
	v_mov_b64_e32 v[44:45], v[20:21]
	v_mov_b64_e32 v[52:53], v[20:21]
	v_mov_b64_e32 v[56:57], v[20:21]
	v_mov_b32_e32 v89, s3
	v_mov_b32_e32 v91, s3
	s_mov_b32 s2, 0x7000000
	s_mov_b32 s7, 0x3a800000
	s_mov_b32 s3, 0x800000
	v_mov_b32_e32 v92, 0x358637bd
	v_mov_b64_e32 v[38:39], v[18:19]
	v_mov_b64_e32 v[46:47], v[18:19]
	v_mov_b64_e32 v[42:43], v[18:19]
	v_mov_b64_e32 v[50:51], v[18:19]
	v_mov_b64_e32 v[54:55], v[18:19]
	s_mov_b32 s10, s76
	v_readlane_b32 s8, v254, 37
	v_readlane_b32 s9, v254, 38
	v_readlane_b32 s11, v254, 40
	v_readlane_b32 s12, v254, 41
	v_readlane_b32 s13, v254, 42
	v_readlane_b32 s14, v254, 43
	v_readlane_b32 s15, v254, 44
	s_waitcnt vmcnt(0)
	s_branch .LBB0_805
.LBB0_804:
	v_lshlrev_b32_e32 v108, 16, v74
	v_and_b32_e32 v109, 0xffff0000, v74
	v_lshlrev_b32_e32 v106, 16, v75
	v_and_b32_e32 v107, 0xffff0000, v75
	v_pk_mul_f32 v[74:75], v[108:109], v[108:109]
	v_lshlrev_b32_e32 v100, 16, v72
	v_add_f32_e32 v74, v74, v75
	v_fmac_f32_e32 v74, v106, v106
	v_pk_fma_f32 v[124:125], v[106:107], v[106:107], v[74:75] op_sel_hi:[1,1,0]
	v_lshlrev_b32_e32 v74, 16, v69
	v_and_b32_e32 v75, 0xffff0000, v69
	v_and_b32_e32 v101, 0xffff0000, v72
	v_mul_f32_e32 v69, 0xbfb8aa3b, v100
	v_exp_f32_e32 v69, v69
	v_mul_f32_e32 v72, 0xbfb8aa3b, v101
	v_exp_f32_e32 v72, v72
	v_and_b32_e32 v99, 0xffff0000, v79
	v_add_f32_e32 v69, 1.0, v69
	v_rcp_f32_e32 v110, v69
	v_add_f32_e32 v69, 1.0, v72
	v_rcp_f32_e32 v111, v69
	v_and_b32_e32 v98, s0, v78
	v_lshlrev_b32_e32 v94, 16, v81
	v_and_b32_e32 v95, 0xffff0000, v81
	v_lshlrev_b32_e32 v96, 16, v80
	v_and_b32_e32 v97, 0xffff0000, v80
	v_lshlrev_b32_e32 v80, 16, v79
	v_mov_b32_e32 v81, v99
	v_pk_mul_f32 v[122:123], v[98:99], v[98:99]
	v_lshlrev_b32_e32 v98, 16, v78
	v_and_b32_e32 v99, 0xffff0000, v78
	v_lshlrev_b32_e32 v78, 16, v77
	v_and_b32_e32 v79, 0xffff0000, v77
	v_lshlrev_b32_e32 v104, 16, v76
	v_and_b32_e32 v105, 0xffff0000, v76
	v_lshlrev_b32_e32 v76, 16, v73
	v_and_b32_e32 v77, 0xffff0000, v73
	v_lshlrev_b32_e32 v72, 16, v68
	v_and_b32_e32 v73, 0xffff0000, v68
	v_pk_mul_f32 v[68:69], v[110:111], v[100:101]
	v_lshlrev_b32_e32 v110, 16, v71
	v_lshlrev_b32_e32 v100, 16, v67
	v_and_b32_e32 v101, 0xffff0000, v67
	v_and_b32_e32 v111, 0xffff0000, v71
; __device__ __forceinline__ unsigned pk2(float lo, float hi) { f32x2 v = {lo, hi}; bf16x2_t b = __builtin_convertvector(v, bf16x2_t); return __builtin_bit_cast(unsigned, b); }
; __device__ __forceinline__ float bflo(unsigned w) { return __uint_as_float(w << 16); }
; __device__ __forceinline__ float bfhi(unsigned w) { return __uint_as_float(w & 0xffff0000u); }
; __device__ __forceinline__ float siluf_(float x) { return x * sigmoidf_(x); }
; __device__ __forceinline__ void mix_norm_rows(bf16* HB, const bf16* Z, const float* ga, const float* gh, int gw, int NGW, int lane) {
;     ...
;         {   float v[16];
; #pragma unroll
;             for (int i = 0; i < 4; ++i) { v[2 * i] = bflo(c[0][i]); v[2 * i + 1] = bfhi(c[0][i]); v[8 + 2 * i] = bflo(c[1][i]); v[8 + 2 * i + 1] = bfhi(c[1][i]); }
;             float ss = 0.f;
; #pragma unroll
;             for (int i = 0; i < 16; ++i) ss += v[i] * v[i];
;             const float rstd = rsqrtf(wave_sum(ss) * (1.0f / 1024.0f) + EPS);
; #pragma unroll
;             for (int i = 0; i < 16; ++i) v[i] *= rstd * gav[i];
;             *(u32x4*)(hr + lane * 8) = (u32x4){pk2(v[0], v[1]), pk2(v[2], v[3]), pk2(v[4], v[5]), pk2(v[6], v[7])};
;             *(u32x4*)(hr + 512 + lane * 8) = (u32x4){pk2(v[8], v[9]), pk2(v[10], v[11]), pk2(v[12], v[13]), pk2(v[14], v[15])}; }
;         {   float v[16], g[16];
; #pragma unroll
;             for (int i = 0; i < 4; ++i) { v[2 * i] = bflo(c[2][i]); v[2 * i + 1] = bfhi(c[2][i]); v[8 + 2 * i] = bflo(c[3][i]); v[8 + 2 * i + 1] = bfhi(c[3][i]);
;                 g[2 * i] = bflo(c[4][i]); g[2 * i + 1] = bfhi(c[4][i]); g[8 + 2 * i] = bflo(c[5][i]); g[8 + 2 * i + 1] = bfhi(c[5][i]); }
;             float ss = 0.f;
; #pragma unroll
;             for (int i = 0; i < 16; ++i) ss += v[i] * v[i];
;             ss += __shfl_xor(ss, 1); ss += __shfl_xor(ss, 2); ss += __shfl_xor(ss, 4);
;             const float rstd = rsqrtf(ss * (1.0f / 128.0f) + EPS);
; #pragma unroll
;             for (int i = 0; i < 16; ++i) v[i] = v[i] * rstd * ghv[i] * siluf_(g[i]);
	v_mul_f32_e32 v67, 0xbfb8aa3b, v110
	v_exp_f32_e32 v67, v67
	v_mul_f32_e32 v71, 0xbfb8aa3b, v111
	v_exp_f32_e32 v71, v71
	v_lshlrev_b32_e32 v134, 16, v70
	v_add_f32_e32 v67, 1.0, v67
	v_rcp_f32_e32 v132, v67
	v_add_f32_e32 v67, 1.0, v71
	v_rcp_f32_e32 v133, v67
	v_and_b32_e32 v135, 0xffff0000, v70
	v_mul_f32_e32 v67, 0xbfb8aa3b, v134
	v_exp_f32_e32 v67, v67
	v_mul_f32_e32 v70, 0xbfb8aa3b, v135
	v_exp_f32_e32 v119, v70
	v_pk_mul_f32 v[70:71], v[132:133], v[110:111]
	v_add_f32_e32 v67, 1.0, v67
	v_rcp_f32_e32 v132, v67
	v_add_f32_e32 v67, 1.0, v119
	v_rcp_f32_e32 v133, v67
	v_lshlrev_b32_e32 v110, 16, v66
	v_and_b32_e32 v111, 0xffff0000, v66
	v_lshlrev_b32_e32 v144, 16, v63
	v_pk_mul_f32 v[66:67], v[132:133], v[134:135]
	v_lshlrev_b32_e32 v132, 16, v61
	v_and_b32_e32 v133, 0xffff0000, v61
	v_mul_f32_e32 v61, 0xbfb8aa3b, v132
	v_exp_f32_e32 v61, v61
	v_mul_f32_e32 v119, 0xbfb8aa3b, v133
	v_exp_f32_e32 v119, v119
	v_lshlrev_b32_e32 v146, 16, v62
	v_add_f32_e32 v61, 1.0, v61
	v_rcp_f32_e32 v138, v61
	v_add_f32_e32 v61, 1.0, v119
	v_rcp_f32_e32 v139, v61
	v_mov_b32_e32 v158, v146
	v_mov_b32_e32 v159, v104
	v_mov_b32_e32 v154, v144
	v_pk_mul_f32 v[132:133], v[138:139], v[132:133]
	v_lshlrev_b32_e32 v138, 16, v60
	v_and_b32_e32 v139, 0xffff0000, v60
	v_mul_f32_e32 v60, 0xbfb8aa3b, v138
	v_mul_f32_e32 v61, 0xbfb8aa3b, v139
	v_exp_f32_e32 v60, v60
	v_exp_f32_e32 v61, v61
	v_mov_b32_e32 v155, v105
	v_lshlrev_b32_e32 v142, 16, v64
	v_add_f32_e32 v60, 1.0, v60
	v_add_f32_e32 v61, 1.0, v61
	v_rcp_f32_e32 v60, v60
	v_rcp_f32_e32 v61, v61
	v_lshlrev_b32_e32 v134, 16, v65
	v_and_b32_e32 v141, 0xffff0000, v65
	v_and_b32_e32 v140, 16, v65
	v_pk_mul_f32 v[138:139], v[60:61], v[138:139]
	v_and_b32_e32 v61, 0xffff0000, v63
	v_and_b32_e32 v60, 16, v63
	v_and_b32_e32 v63, 0xffff0000, v62
	v_and_b32_e32 v62, s0, v62
	v_pk_mul_f32 v[148:149], v[62:63], v[62:63]
	v_pk_mov_b32 v[156:157], v[60:61], v[78:79] op_sel:[1,0]
	v_mov_b32_e32 v124, v149
	v_pk_fma_f32 v[124:125], v[158:159], v[158:159], v[124:125]
	v_and_b32_e32 v65, 0xffff0000, v64
	v_pk_fma_f32 v[124:125], v[154:155], v[154:155], v[124:125]
	v_and_b32_e32 v64, 16, v64
	v_mov_b32_e32 v152, v142
	v_mov_b32_e32 v153, v79
	v_pk_fma_f32 v[124:125], v[156:157], v[156:157], v[124:125]
	v_mov_b32_e32 v143, v65
	v_pk_mov_b32 v[64:65], v[64:65], v[98:99] op_sel:[1,0]
	v_pk_fma_f32 v[124:125], v[152:153], v[152:153], v[124:125]
	v_mov_b32_e32 v150, v134
	v_mov_b32_e32 v151, v99
	v_pk_fma_f32 v[64:65], v[64:65], v[64:65], v[124:125]
	v_pk_mul_f32 v[136:137], v[110:111], v[110:111]
	v_mov_b32_e32 v135, v141
	v_pk_mov_b32 v[140:141], v[140:141], v[80:81] op_sel:[1,0]
	v_pk_fma_f32 v[64:65], v[150:151], v[150:151], v[64:65]
	v_pk_mul_f32 v[120:121], v[96:97], v[96:97]
	v_pk_fma_f32 v[64:65], v[140:141], v[140:141], v[64:65]
	v_mov_b32_e32 v122, v136
	v_pk_mul_f32 v[130:131], v[100:101], v[100:101]
	v_pk_add_f32 v[64:65], v[122:123], v[64:65]
	v_pk_mov_b32 v[122:123], v[136:137], v[120:121] op_sel:[1,0]
	v_pk_mul_f32 v[112:113], v[94:95], v[94:95]
	v_pk_add_f32 v[64:65], v[122:123], v[64:65]
	v_mov_b32_e32 v120, v130
	v_pk_mul_f32 v[128:129], v[72:73], v[72:73]
	v_pk_add_f32 v[64:65], v[120:121], v[64:65]
	v_pk_mov_b32 v[120:121], v[130:131], v[112:113] op_sel:[1,0]
	v_mov_b32_e32 v112, v128
	v_pk_add_f32 v[64:65], v[120:121], v[64:65]
	v_pk_mul_f32 v[126:127], v[74:75], v[74:75]
	v_pk_add_f32 v[64:65], v[112:113], v[64:65]
	ds_bpermute_b32 v113, v93, v65
	v_mov_b32_e32 v112, v129
	v_lshlrev_b32_e32 v60, 16, v59
	v_mul_f32_e32 v62, 0xbfb8aa3b, v60
	v_exp_f32_e32 v62, v62
	s_waitcnt lgkmcnt(0)
	v_pk_add_f32 v[64:65], v[112:113], v[64:65]
	ds_bpermute_b32 v113, v114, v65
	v_mov_b32_e32 v112, v126
	v_mov_b32_e32 v145, v61
	v_and_b32_e32 v61, 0xffff0000, v59
	v_add_f32_e32 v59, 1.0, v62
	s_waitcnt lgkmcnt(0)
	v_pk_add_f32 v[64:65], v[112:113], v[64:65]
	ds_bpermute_b32 v113, v115, v65
	v_mov_b32_e32 v112, v127
	v_rcp_f32_e32 v120, v59
	v_mul_f32_e32 v59, 0xbfb8aa3b, v61
	v_exp_f32_e32 v59, v59
	s_waitcnt lgkmcnt(0)
	v_pk_add_f32 v[64:65], v[112:113], v[64:65]
	ds_bpermute_b32 v113, v116, v65
	ds_bpermute_b32 v112, v93, v64
	v_add_f32_e32 v59, 1.0, v59
	v_rcp_f32_e32 v121, v59
	v_lshlrev_b32_e32 v122, 16, v58
	v_and_b32_e32 v123, 0xffff0000, v58
	s_waitcnt lgkmcnt(0)
	v_pk_add_f32 v[58:59], v[64:65], v[112:113]
	ds_bpermute_b32 v65, v117, v59
	ds_bpermute_b32 v64, v114, v58
	v_mul_f32_e32 v62, 0xbfb8aa3b, v122
	v_exp_f32_e32 v62, v62
	v_mul_f32_e32 v112, 0xbfb8aa3b, v123
	v_exp_f32_e32 v113, v112
	s_waitcnt lgkmcnt(0)
	v_pk_add_f32 v[58:59], v[58:59], v[64:65]
	ds_bpermute_b32 v65, v118, v59
	ds_bpermute_b32 v64, v115, v58
	v_add_f32_e32 v62, 1.0, v62
	v_rcp_f32_e32 v112, v62
	v_add_f32_e32 v62, 1.0, v113
	v_rcp_f32_e32 v113, v62
	s_waitcnt lgkmcnt(0)
; __device__ __forceinline__ unsigned pk2(float lo, float hi) { f32x2 v = {lo, hi}; bf16x2_t b = __builtin_convertvector(v, bf16x2_t); return __builtin_bit_cast(unsigned, b); }
; __device__ __forceinline__ float bflo(unsigned w) { return __uint_as_float(w << 16); }
; __device__ __forceinline__ float bfhi(unsigned w) { return __uint_as_float(w & 0xffff0000u); }
; __device__ __forceinline__ float siluf_(float x) { return x * sigmoidf_(x); }
; __device__ __forceinline__ void mix_norm_rows(bf16* HB, const bf16* Z, const float* ga, const float* gh, int gw, int NGW, int lane) {
;     ...
;             for (int i = 0; i < 4; ++i) { v[2 * i] = bflo(c[0][i]); v[2 * i + 1] = bfhi(c[0][i]); v[8 + 2 * i] = bflo(c[1][i]); v[8 + 2 * i + 1] = bfhi(c[1][i]); }
;             float ss = 0.f;
; #pragma unroll
;             for (int i = 0; i < 16; ++i) ss += v[i] * v[i];
;             const float rstd = rsqrtf(wave_sum(ss) * (1.0f / 1024.0f) + EPS);
; #pragma unroll
;             for (int i = 0; i < 16; ++i) v[i] *= rstd * gav[i];
;             *(u32x4*)(hr + lane * 8) = (u32x4){pk2(v[0], v[1]), pk2(v[2], v[3]), pk2(v[4], v[5]), pk2(v[6], v[7])};
;             *(u32x4*)(hr + 512 + lane * 8) = (u32x4){pk2(v[8], v[9]), pk2(v[10], v[11]), pk2(v[12], v[13]), pk2(v[14], v[15])}; }
;         {   float v[16], g[16];
; #pragma unroll
;             for (int i = 0; i < 4; ++i) { v[2 * i] = bflo(c[2][i]); v[2 * i + 1] = bfhi(c[2][i]); v[8 + 2 * i] = bflo(c[3][i]); v[8 + 2 * i + 1] = bfhi(c[3][i]);
;                 g[2 * i] = bflo(c[4][i]); g[2 * i + 1] = bfhi(c[4][i]); g[8 + 2 * i] = bflo(c[5][i]); g[8 + 2 * i + 1] = bfhi(c[5][i]); }
;             float ss = 0.f;
; #pragma unroll
;             for (int i = 0; i < 16; ++i) ss += v[i] * v[i];
;             ss += __shfl_xor(ss, 1); ss += __shfl_xor(ss, 2); ss += __shfl_xor(ss, 4);
;             const float rstd = rsqrtf(ss * (1.0f / 128.0f) + EPS);
; #pragma unroll
;             for (int i = 0; i < 16; ++i) v[i] = v[i] * rstd * ghv[i] * siluf_(g[i]);
;             *(u32x4*)(hr + 1024 + lane * 16) = (u32x4){pk2(v[0], v[1]), pk2(v[2], v[3]), pk2(v[4], v[5]), pk2(v[6], v[7])};
;             *(u32x4*)(hr + 1024 + lane * 16 + 8) = (u32x4){pk2(v[8], v[9]), pk2(v[10], v[11]), pk2(v[12], v[13]), pk2(v[14], v[15])}; }
; #pragma unroll
;         for (int i = 0; i < 6; ++i) c[i] = n[i];
;         row = nrow;
	v_pk_add_f32 v[58:59], v[58:59], v[64:65]
	v_mov_b32_e32 v147, v63
	v_pk_fma_f32 v[64:65], v[58:59], s[6:7], v[92:93] op_sel_hi:[1,1,0]
	v_pk_mul_f32 v[62:63], v[112:113], v[122:123]
	v_mul_f32_e32 v58, 0x4b800000, v65
	v_cmp_gt_f32_e32 vcc, s3, v65
	v_pk_mul_f32 v[120:121], v[120:121], v[60:61]
	v_lshl_add_u64 v[102:103], s[92:93], 0, v[84:85]
	v_cndmask_b32_e32 v58, v65, v58, vcc
	v_rsq_f32_e32 v58, v58
	v_lshl_add_u64 v[84:85], v[84:85], 0, s[0:1]
	v_lshl_add_u64 v[86:87], v[86:87], 0, s[4:5]
	v_lshl_add_u64 v[88:89], v[88:89], 0, s[0:1]
	v_mul_f32_e32 v59, 0x45800000, v58
	v_cndmask_b32_e32 v112, v58, v59, vcc
	v_pk_mul_f32 v[60:61], v[8:9], v[112:113] op_sel_hi:[1,0]
	v_pk_mul_f32 v[58:59], v[6:7], v[112:113] op_sel_hi:[1,0]
	v_pk_mul_f32 v[60:61], v[60:61], v[106:107]
	v_pk_mul_f32 v[106:107], v[2:3], v[112:113] op_sel_hi:[1,0]
	v_pk_mul_f32 v[58:59], v[58:59], v[108:109]
	v_pk_mul_f32 v[104:105], v[106:107], v[104:105]
	v_pk_mul_f32 v[106:107], v[4:5], v[112:113] op_sel_hi:[1,0]
	v_cvt_pk_bf16_f32 v58, v58, v59
	v_pk_mul_f32 v[78:79], v[106:107], v[78:79]
	v_pk_mul_f32 v[106:107], v[14:15], v[112:113] op_sel_hi:[1,0]
	v_cvt_pk_bf16_f32 v59, v60, v61
	v_cvt_pk_bf16_f32 v61, v78, v79
	v_add_co_u32_e32 v78, vcc, s2, v102
	v_pk_mul_f32 v[98:99], v[106:107], v[98:99]
	v_pk_mul_f32 v[106:107], v[16:17], v[112:113] op_sel_hi:[1,0]
	v_cvt_pk_bf16_f32 v60, v104, v105
	v_addc_co_u32_e32 v79, vcc, 0, v103, vcc
	v_pk_mul_f32 v[80:81], v[106:107], v[80:81]
	v_pk_mul_f32 v[106:107], v[10:11], v[112:113] op_sel_hi:[1,0]
	global_store_dwordx4 v[78:79], v[58:61], off
	v_cmp_gt_f32_e32 vcc, s3, v64
	v_pk_mul_f32 v[96:97], v[106:107], v[96:97]
	v_mul_f32_e32 v61, 0x4b800000, v64
	v_cndmask_b32_e32 v61, v64, v61, vcc
	v_cvt_pk_bf16_f32 v60, v96, v97
	v_rsq_f32_e32 v96, v61
	v_cvt_pk_bf16_f32 v59, v80, v81
	v_pk_mul_f32 v[80:81], v[12:13], v[112:113] op_sel_hi:[1,0]
	v_cvt_pk_bf16_f32 v58, v98, v99
	v_pk_mul_f32 v[64:65], v[80:81], v[94:95]
	v_lshl_add_u64 v[90:91], v[90:91], 0, s[0:1]
	v_cvt_pk_bf16_f32 v61, v64, v65
	global_store_dwordx4 v[78:79], v[58:61], off offset:1024
	s_nop 1
	v_mul_f32_e32 v58, 0x45800000, v96
	v_cndmask_b32_e32 v64, v96, v58, vcc
	v_pk_mul_f32 v[80:81], v[64:65], v[110:111] op_sel_hi:[0,1]
	v_pk_mul_f32 v[58:59], v[64:65], v[146:147] op_sel_hi:[0,1]
	v_pk_mul_f32 v[80:81], v[26:27], v[80:81]
	v_pk_mul_f32 v[58:59], v[34:35], v[58:59]
	v_pk_mul_f32 v[66:67], v[66:67], v[80:81]
	v_pk_mul_f32 v[80:81], v[64:65], v[100:101] op_sel_hi:[0,1]
	v_pk_mul_f32 v[58:59], v[62:63], v[58:59]
	v_pk_mul_f32 v[60:61], v[64:65], v[144:145] op_sel_hi:[0,1]
	v_pk_mul_f32 v[62:63], v[64:65], v[142:143] op_sel_hi:[0,1]
	v_pk_mul_f32 v[78:79], v[64:65], v[134:135] op_sel_hi:[0,1]
	v_pk_mul_f32 v[80:81], v[28:29], v[80:81]
	v_pk_mul_f32 v[72:73], v[64:65], v[72:73] op_sel_hi:[0,1]
	v_mul_f32_e32 v65, 0xbfb8aa3b, v76
	v_pk_mul_f32 v[70:71], v[70:71], v[80:81]
	v_exp_f32_e32 v65, v65
	v_mul_f32_e32 v80, 0xbfb8aa3b, v77
	v_exp_f32_e32 v80, v80
	v_pk_mul_f32 v[72:73], v[22:23], v[72:73]
	v_add_f32_e32 v65, 1.0, v65
	v_pk_mul_f32 v[60:61], v[36:37], v[60:61]
	v_pk_mul_f32 v[62:63], v[30:31], v[62:63]
	v_pk_mul_f32 v[68:69], v[68:69], v[72:73]
	v_rcp_f32_e32 v72, v65
	v_add_f32_e32 v65, 1.0, v80
	v_pk_mul_f32 v[60:61], v[120:121], v[60:61]
	v_pk_mul_f32 v[62:63], v[138:139], v[62:63]
	v_rcp_f32_e32 v73, v65
	v_pk_mul_f32 v[78:79], v[32:33], v[78:79]
	v_cvt_pk_bf16_f32 v58, v58, v59
	v_cvt_pk_bf16_f32 v59, v60, v61
	v_cvt_pk_bf16_f32 v60, v62, v63
	v_lshl_add_u64 v[62:63], s[92:93], 0, v[82:83]
	v_pk_mul_f32 v[78:79], v[132:133], v[78:79]
	v_add_co_u32_e32 v62, vcc, s2, v62
	v_cvt_pk_bf16_f32 v61, v78, v79
	s_nop 0
	v_addc_co_u32_e32 v63, vcc, 0, v63, vcc
	v_pk_mul_f32 v[64:65], v[64:65], v[74:75] op_sel_hi:[0,1]
	global_store_dwordx4 v[62:63], v[58:61], off offset:2048
	v_pk_mul_f32 v[64:65], v[24:25], v[64:65]
	s_waitcnt vmcnt(3)
	v_mov_b64_e32 v[80:81], v[40:41]
	v_cvt_pk_bf16_f32 v58, v66, v67
	v_pk_mul_f32 v[66:67], v[72:73], v[76:77]
	v_cvt_pk_bf16_f32 v59, v70, v71
	v_pk_mul_f32 v[64:65], v[66:67], v[64:65]
	v_cvt_pk_bf16_f32 v60, v68, v69
	v_cvt_pk_bf16_f32 v61, v64, v65
	global_store_dwordx4 v[62:63], v[58:61], off offset:2064
	v_mov_b64_e32 v[76:77], v[20:21]
	v_mov_b64_e32 v[64:65], v[48:49]
	v_mov_b64_e32 v[68:69], v[44:45]
	v_mov_b64_e32 v[60:61], v[52:53]
	v_mov_b64_e32 v[72:73], v[56:57]
	v_lshl_add_u64 v[82:83], v[82:83], 0, s[0:1]
	s_andn2_b64 vcc, exec, s[8:9]
	v_mov_b64_e32 v[74:75], v[18:19]
	v_mov_b64_e32 v[78:79], v[38:39]
	v_mov_b64_e32 v[62:63], v[46:47]
	v_mov_b64_e32 v[66:67], v[42:43]
	v_mov_b64_e32 v[58:59], v[50:51]
	v_mov_b64_e32 v[70:71], v[54:55]
	s_cbranch_vccz .LBB0_807
